# P6 readout: per-column constants fetched once per wave, operand loads two tasks ahead (two register sets)
# baseline (speedup 1.0000x reference)
.LBB0_784:
	s_or_b64 exec, exec, s[6:7]
	v_readlane_b32 s0, v255, 10
	v_readlane_b32 s1, v255, 11
	s_waitcnt lgkmcnt(0)
	v_mov_b32_e32 v0, v254
	s_waitcnt vmcnt(0)
	v_mov_b64_e32 v[2:3], s[0:1]
	s_barrier
	flat_load_dwordx2 v[4:5], v[2:3] offset:200 sc0 sc1
	flat_load_dwordx2 v[6:7], v[2:3] offset:208 sc0 sc1
	flat_load_dwordx2 v[8:9], v[2:3] offset:216 sc0 sc1
	flat_load_dwordx2 v[2:3], v[2:3] offset:224 sc0 sc1
	s_waitcnt vmcnt(0)
	s_add_u32 s8, s26, 0xf200000
	v_readfirstlane_b32 s0, v0
	s_addc_u32 s9, s27, 0
	s_ashr_i32 s0, s0, 6
	v_readlane_b32 s1, v255, 6
	s_add_i32 s20, s0, s1
	s_cmp_lt_i32 s20, 0x10000
	s_waitcnt lgkmcnt(0)
	v_readfirstlane_b32 s11, v5
	v_readfirstlane_b32 s10, v4
	v_readfirstlane_b32 s13, v7
	v_readfirstlane_b32 s12, v6
	v_readfirstlane_b32 s15, v9
	v_readfirstlane_b32 s14, v8
	v_readfirstlane_b32 s17, v3
	v_readfirstlane_b32 s16, v2
	s_cbranch_scc0 .LBB0_787
	s_add_u32 s18, s26, 0xb200000
	s_addc_u32 s19, s27, 0
	v_lshlrev_b32_e32 v0, 2, v0
	s_lshl_b32 s1, s2, 11
	s_lshl_b32 s0, s0, 8
	v_and_b32_e32 v2, 0xfc, v0
	s_add_i32 s21, s1, s0
	s_lshl_b32 s23, s30, 11
	v_mov_b32_e32 v3, 0x3a27c5ac
	s_mov_b32 s24, 0xf800000
	v_mov_b32_e32 v4, 0x260
	v_mov_b32_e32 v1, 0
	s_movk_i32 s25, 0x1000
	s_and_b32 s0, s21, 0x700
	v_or_b32_e32 v124, s0, v2
	v_lshlrev_b32_e32 v120, 2, v124
	global_load_dwordx4 v[60:63], v120, s[14:15]
	global_load_dwordx4 v[64:67], v120, s[16:17]
	global_load_dwordx4 v[68:71], v120, s[10:11]
	global_load_dwordx4 v[72:75], v120, s[12:13]
	s_min_i32 s0, s20, 0xffff
	s_ashr_i32 s0, s0, 3
	s_lshl_b32 s1, s0, 11
	s_lshl_b32 s5, s0, 12
	v_add_u32_e32 v121, s1, v124
	v_add_u32_e32 v122, s5, v124
	v_lshlrev_b32_e32 v98, 1, v121
	v_lshlrev_b32_e32 v121, 2, v121
	v_lshlrev_b32_e32 v122, 1, v122
	v_add_u32_e32 v123, 0x1000, v122
	global_load_dwordx2 v[80:81], v98, s[38:39]
	global_load_dwordx2 v[82:83], v98, s[18:19]
	global_load_dwordx2 v[84:85], v98, s[66:67]
	global_load_dwordx2 v[86:87], v98, s[68:69]
	global_load_dwordx2 v[88:89], v98, s[56:57]
	global_load_dwordx4 v[90:93], v121, s[48:49]
	global_load_dwordx2 v[94:95], v122, s[52:53]
	global_load_dwordx2 v[96:97], v123, s[52:53]
	s_add_i32 s20, s20, s22
	s_min_i32 s0, s20, 0xffff
	s_ashr_i32 s0, s0, 3
	s_lshl_b32 s1, s0, 11
	s_lshl_b32 s5, s0, 12
	v_add_u32_e32 v121, s1, v124
	v_add_u32_e32 v122, s5, v124
	v_lshlrev_b32_e32 v118, 1, v121
	v_lshlrev_b32_e32 v121, 2, v121
	v_lshlrev_b32_e32 v122, 1, v122
	v_add_u32_e32 v123, 0x1000, v122
	global_load_dwordx2 v[100:101], v118, s[38:39]
	global_load_dwordx2 v[102:103], v118, s[18:19]
	global_load_dwordx2 v[104:105], v118, s[66:67]
	global_load_dwordx2 v[106:107], v118, s[68:69]
	global_load_dwordx2 v[108:109], v118, s[56:57]
	global_load_dwordx4 v[110:113], v121, s[48:49]
	global_load_dwordx2 v[114:115], v122, s[52:53]
	global_load_dwordx2 v[116:117], v123, s[52:53]
	s_add_i32 s20, s20, s22
	s_movk_i32 s4, 16
.Lp6_loop:
	s_waitcnt vmcnt(8)
	v_mov_b64_e32 v[28:29], v[80:81]
	v_mov_b64_e32 v[30:31], v[82:83]
	v_mov_b64_e32 v[32:33], v[84:85]
	v_mov_b64_e32 v[34:35], v[86:87]
	v_mov_b64_e32 v[36:37], v[88:89]
	v_mov_b64_e32 v[22:23], v[90:91]
	v_mov_b64_e32 v[24:25], v[92:93]
	v_mov_b64_e32 v[40:41], v[94:95]
	v_mov_b64_e32 v[38:39], v[96:97]
	v_mov_b32_e32 v26, v98
	v_mov_b64_e32 v[6:7], v[60:61]
	v_mov_b64_e32 v[8:9], v[62:63]
	v_mov_b64_e32 v[10:11], v[64:65]
	v_mov_b64_e32 v[12:13], v[66:67]
	v_mov_b64_e32 v[14:15], v[68:69]
	v_mov_b64_e32 v[16:17], v[70:71]
	v_mov_b64_e32 v[18:19], v[72:73]
	v_mov_b64_e32 v[20:21], v[74:75]
	s_min_i32 s0, s20, 0xffff
	s_ashr_i32 s0, s0, 3
	s_lshl_b32 s1, s0, 11
	s_lshl_b32 s5, s0, 12
	v_add_u32_e32 v121, s1, v124
	v_add_u32_e32 v122, s5, v124
	v_lshlrev_b32_e32 v98, 1, v121
	v_lshlrev_b32_e32 v121, 2, v121
	v_lshlrev_b32_e32 v122, 1, v122
	v_add_u32_e32 v123, 0x1000, v122
	global_load_dwordx2 v[80:81], v98, s[38:39]
	global_load_dwordx2 v[82:83], v98, s[18:19]
	global_load_dwordx2 v[84:85], v98, s[66:67]
	global_load_dwordx2 v[86:87], v98, s[68:69]
	global_load_dwordx2 v[88:89], v98, s[56:57]
	global_load_dwordx4 v[90:93], v121, s[48:49]
	global_load_dwordx2 v[94:95], v122, s[52:53]
	global_load_dwordx2 v[96:97], v123, s[52:53]
	s_add_i32 s20, s20, s22
	v_lshlrev_b32_e32 v44, 16, v28
	v_and_b32_e32 v45, 0xffff0000, v28
	v_lshlrev_b32_e32 v28, 16, v29
	v_and_b32_e32 v29, 0xffff0000, v29
	v_lshlrev_b32_e32 v46, 16, v30
	v_and_b32_e32 v47, 0xffff0000, v30
	v_lshlrev_b32_e32 v30, 16, v31
	v_and_b32_e32 v31, 0xffff0000, v31
	v_pk_add_f32 v[28:29], v[28:29], v[30:31]
	v_pk_add_f32 v[30:31], v[44:45], v[46:47]
	v_lshlrev_b32_e32 v42, 16, v40
	v_add_f32_e32 v0, v30, v31
	v_and_b32_e32 v43, 0xffff0000, v40
	v_lshlrev_b32_e32 v44, 16, v38
	v_and_b32_e32 v45, 0xffff0000, v38
	v_add_f32_e32 v0, v28, v0
	v_lshlrev_b32_e32 v40, 16, v41
	v_and_b32_e32 v41, 0xffff0000, v41
	v_lshlrev_b32_e32 v38, 16, v39
	v_and_b32_e32 v39, 0xffff0000, v39
	v_pk_add_f32 v[42:43], v[42:43], v[44:45]
	v_add_f32_e32 v0, v29, v0
	v_pk_add_f32 v[38:39], v[40:41], v[38:39]
	v_pk_add_f32 v[40:41], v[42:43], -2.0 op_sel_hi:[1,0]
	v_add_f32_dpp v0, v0, v0 quad_perm:[1,0,3,2] row_mask:0xf bank_mask:0xf bound_ctrl:1
	v_pk_add_f32 v[38:39], v[38:39], -2.0 op_sel_hi:[1,0]
	s_waitcnt lgkmcnt(0)
	v_pk_fma_f32 v[14:15], v[14:15], v[40:41], 2.0 op_sel_hi:[1,1,0]
	v_add_f32_dpp v0, v0, v0 quad_perm:[2,3,0,1] row_mask:0xf bank_mask:0xf bound_ctrl:1
	v_lshlrev_b32_e32 v48, 16, v32
	v_and_b32_e32 v49, 0xffff0000, v32
	v_pk_fma_f32 v[16:17], v[16:17], v[38:39], 2.0 op_sel_hi:[1,1,0]
	v_pk_mul_f32 v[14:15], v[22:23], v[14:15]
	v_add_f32_dpp v0, v0, v0 row_half_mirror row_mask:0xf bank_mask:0xf bound_ctrl:1
	v_lshlrev_b32_e32 v32, 16, v33
	v_and_b32_e32 v33, 0xffff0000, v33
	v_pk_mul_f32 v[16:17], v[24:25], v[16:17]
	v_pk_mul_f32 v[14:15], v[14:15], v[48:49]
	v_add_f32_dpp v0, v0, v0 row_ror:8 row_mask:0xf bank_mask:0xf bound_ctrl:1
	v_pk_mul_f32 v[16:17], v[16:17], v[32:33]
	v_pk_mul_f32 v[14:15], v[18:19], v[14:15]
	v_fmamk_f32 v31, v0, 0xbc800000, v31
	v_fmac_f32_e32 v30, 0xbc800000, v0
	v_pk_mul_f32 v[16:17], v[20:21], v[16:17]
	v_add_f32_e32 v5, v14, v15
	v_fmamk_f32 v29, v0, 0xbc800000, v29
	v_fmac_f32_e32 v28, 0xbc800000, v0
	v_pk_mul_f32 v[18:19], v[30:31], v[30:31]
	v_add_f32_e32 v0, v16, v5
	v_pk_mul_f32 v[14:15], v[28:29], v[28:29]
	v_add_f32_e32 v5, v18, v19
	v_add_f32_e32 v5, v14, v5
	v_add_f32_e32 v5, v15, v5
	v_add_f32_e32 v0, v17, v0
	v_lshlrev_b32_e32 v50, 16, v34
	v_add_f32_dpp v5, v5, v5 quad_perm:[1,0,3,2] row_mask:0xf bank_mask:0xf bound_ctrl:1
	v_add_f32_dpp v0, v0, v0 quad_perm:[1,0,3,2] row_mask:0xf bank_mask:0xf bound_ctrl:1
	v_and_b32_e32 v51, 0xffff0000, v34
	v_add_f32_dpp v5, v5, v5 quad_perm:[2,3,0,1] row_mask:0xf bank_mask:0xf bound_ctrl:1
	v_add_f32_dpp v0, v0, v0 quad_perm:[2,3,0,1] row_mask:0xf bank_mask:0xf bound_ctrl:1
	v_lshlrev_b32_e32 v34, 16, v35
	v_add_f32_dpp v5, v5, v5 row_half_mirror row_mask:0xf bank_mask:0xf bound_ctrl:1
	v_add_f32_dpp v0, v0, v0 row_half_mirror row_mask:0xf bank_mask:0xf bound_ctrl:1
	v_and_b32_e32 v35, 0xffff0000, v35
	v_add_f32_dpp v5, v5, v5 row_ror:8 row_mask:0xf bank_mask:0xf bound_ctrl:1
	v_fmamk_f32 v5, v5, 0x3c800000, v3
	v_mul_f32_e32 v14, 0x4f800000, v5
	v_cmp_gt_f32_e32 vcc, s24, v5
	v_add_f32_dpp v0, v0, v0 row_ror:8 row_mask:0xf bank_mask:0xf bound_ctrl:1
	v_lshlrev_b32_e32 v52, 16, v36
	v_cndmask_b32_e32 v5, v5, v14, vcc
	v_sqrt_f32_e32 v14, v5
	v_and_b32_e32 v53, 0xffff0000, v36
	v_lshlrev_b32_e32 v36, 16, v37
	v_and_b32_e32 v37, 0xffff0000, v37
	v_add_u32_e32 v15, -1, v14
	v_add_u32_e32 v16, 1, v14
	v_fma_f32 v17, -v15, v14, v5
	v_fma_f32 v18, -v16, v14, v5
	v_cmp_ge_f32_e64 s[6:7], 0, v17
	s_nop 1
	v_cndmask_b32_e64 v14, v14, v15, s[6:7]
	v_cmp_lt_f32_e64 s[6:7], 0, v18
	s_nop 1
	v_cndmask_b32_e64 v14, v14, v16, s[6:7]
	v_mul_f32_e32 v15, 0x37800000, v14
	v_cndmask_b32_e32 v14, v14, v15, vcc
	v_cmp_class_f32_e32 vcc, v5, v4
	s_nop 1
	v_cndmask_b32_e32 v5, v14, v5, vcc
	v_div_scale_f32 v14, s[0:1], v5, v5, 1.0
	v_rcp_f32_e32 v16, v14
	v_div_scale_f32 v15, vcc, 1.0, v5, 1.0
	v_fma_f32 v17, -v14, v16, 1.0
	v_fmac_f32_e32 v16, v17, v16
	v_mul_f32_e32 v17, v15, v16
	v_fma_f32 v18, -v14, v17, v15
	v_fmac_f32_e32 v17, v18, v16
	v_fma_f32 v14, -v14, v17, v15
	v_div_fmas_f32 v14, v14, v16, v17
	v_div_fixup_f32 v14, v14, v5, 1.0
	v_pk_mul_f32 v[16:17], v[30:31], v[14:15] op_sel_hi:[1,0]
	v_pk_mul_f32 v[14:15], v[28:29], v[14:15] op_sel_hi:[1,0]
	v_pk_fma_f32 v[6:7], v[6:7], v[16:17], v[10:11]
	v_pk_fma_f32 v[8:9], v[8:9], v[14:15], v[12:13]
	v_pk_fma_f32 v[6:7], v[0:1], v[50:51], v[6:7] op_sel_hi:[0,1,1]
	v_pk_fma_f32 v[8:9], v[0:1], v[34:35], v[8:9] op_sel_hi:[0,1,1]
	v_pk_mul_f32 v[6:7], v[6:7], v[52:53]
	v_pk_mul_f32 v[8:9], v[8:9], v[36:37]
	s_nop 1
	v_cvt_pk_bf16_f32 v6, v6, v7
	s_nop 0
	s_nop 1
	v_cvt_pk_bf16_f32 v7, v8, v9
	global_store_dwordx2 v26, v[6:7], s[8:9]
	s_waitcnt vmcnt(8)
	v_mov_b64_e32 v[28:29], v[100:101]
	v_mov_b64_e32 v[30:31], v[102:103]
	v_mov_b64_e32 v[32:33], v[104:105]
	v_mov_b64_e32 v[34:35], v[106:107]
	v_mov_b64_e32 v[36:37], v[108:109]
	v_mov_b64_e32 v[22:23], v[110:111]
	v_mov_b64_e32 v[24:25], v[112:113]
	v_mov_b64_e32 v[40:41], v[114:115]
	v_mov_b64_e32 v[38:39], v[116:117]
	v_mov_b32_e32 v26, v118
	v_mov_b64_e32 v[6:7], v[60:61]
	v_mov_b64_e32 v[8:9], v[62:63]
	v_mov_b64_e32 v[10:11], v[64:65]
	v_mov_b64_e32 v[12:13], v[66:67]
	v_mov_b64_e32 v[14:15], v[68:69]
	v_mov_b64_e32 v[16:17], v[70:71]
	v_mov_b64_e32 v[18:19], v[72:73]
	v_mov_b64_e32 v[20:21], v[74:75]
	s_min_i32 s0, s20, 0xffff
	s_ashr_i32 s0, s0, 3
	s_lshl_b32 s1, s0, 11
	s_lshl_b32 s5, s0, 12
	v_add_u32_e32 v121, s1, v124
	v_add_u32_e32 v122, s5, v124
	v_lshlrev_b32_e32 v118, 1, v121
	v_lshlrev_b32_e32 v121, 2, v121
	v_lshlrev_b32_e32 v122, 1, v122
	v_add_u32_e32 v123, 0x1000, v122
	global_load_dwordx2 v[100:101], v118, s[38:39]
	global_load_dwordx2 v[102:103], v118, s[18:19]
	global_load_dwordx2 v[104:105], v118, s[66:67]
	global_load_dwordx2 v[106:107], v118, s[68:69]
	global_load_dwordx2 v[108:109], v118, s[56:57]
	global_load_dwordx4 v[110:113], v121, s[48:49]
	global_load_dwordx2 v[114:115], v122, s[52:53]
	global_load_dwordx2 v[116:117], v123, s[52:53]
	s_add_i32 s20, s20, s22
	v_lshlrev_b32_e32 v44, 16, v28
	v_and_b32_e32 v45, 0xffff0000, v28
	v_lshlrev_b32_e32 v28, 16, v29
	v_and_b32_e32 v29, 0xffff0000, v29
	v_lshlrev_b32_e32 v46, 16, v30
	v_and_b32_e32 v47, 0xffff0000, v30
	v_lshlrev_b32_e32 v30, 16, v31
	v_and_b32_e32 v31, 0xffff0000, v31
	v_pk_add_f32 v[28:29], v[28:29], v[30:31]
	v_pk_add_f32 v[30:31], v[44:45], v[46:47]
	v_lshlrev_b32_e32 v42, 16, v40
	v_add_f32_e32 v0, v30, v31
	v_and_b32_e32 v43, 0xffff0000, v40
	v_lshlrev_b32_e32 v44, 16, v38
	v_and_b32_e32 v45, 0xffff0000, v38
	v_add_f32_e32 v0, v28, v0
	v_lshlrev_b32_e32 v40, 16, v41
	v_and_b32_e32 v41, 0xffff0000, v41
	v_lshlrev_b32_e32 v38, 16, v39
	v_and_b32_e32 v39, 0xffff0000, v39
	v_pk_add_f32 v[42:43], v[42:43], v[44:45]
	v_add_f32_e32 v0, v29, v0
	v_pk_add_f32 v[38:39], v[40:41], v[38:39]
	v_pk_add_f32 v[40:41], v[42:43], -2.0 op_sel_hi:[1,0]
	v_add_f32_dpp v0, v0, v0 quad_perm:[1,0,3,2] row_mask:0xf bank_mask:0xf bound_ctrl:1
	v_pk_add_f32 v[38:39], v[38:39], -2.0 op_sel_hi:[1,0]
	s_waitcnt lgkmcnt(0)
	v_pk_fma_f32 v[14:15], v[14:15], v[40:41], 2.0 op_sel_hi:[1,1,0]
	v_add_f32_dpp v0, v0, v0 quad_perm:[2,3,0,1] row_mask:0xf bank_mask:0xf bound_ctrl:1
	v_lshlrev_b32_e32 v48, 16, v32
	v_and_b32_e32 v49, 0xffff0000, v32
	v_pk_fma_f32 v[16:17], v[16:17], v[38:39], 2.0 op_sel_hi:[1,1,0]
	v_pk_mul_f32 v[14:15], v[22:23], v[14:15]
	v_add_f32_dpp v0, v0, v0 row_half_mirror row_mask:0xf bank_mask:0xf bound_ctrl:1
	v_lshlrev_b32_e32 v32, 16, v33
	v_and_b32_e32 v33, 0xffff0000, v33
	v_pk_mul_f32 v[16:17], v[24:25], v[16:17]
	v_pk_mul_f32 v[14:15], v[14:15], v[48:49]
	v_add_f32_dpp v0, v0, v0 row_ror:8 row_mask:0xf bank_mask:0xf bound_ctrl:1
	v_pk_mul_f32 v[16:17], v[16:17], v[32:33]
	v_pk_mul_f32 v[14:15], v[18:19], v[14:15]
	v_fmamk_f32 v31, v0, 0xbc800000, v31
	v_fmac_f32_e32 v30, 0xbc800000, v0
	v_pk_mul_f32 v[16:17], v[20:21], v[16:17]
	v_add_f32_e32 v5, v14, v15
	v_fmamk_f32 v29, v0, 0xbc800000, v29
	v_fmac_f32_e32 v28, 0xbc800000, v0
	v_pk_mul_f32 v[18:19], v[30:31], v[30:31]
	v_add_f32_e32 v0, v16, v5
	v_pk_mul_f32 v[14:15], v[28:29], v[28:29]
	v_add_f32_e32 v5, v18, v19
	v_add_f32_e32 v5, v14, v5
	v_add_f32_e32 v5, v15, v5
	v_add_f32_e32 v0, v17, v0
	v_lshlrev_b32_e32 v50, 16, v34
	v_add_f32_dpp v5, v5, v5 quad_perm:[1,0,3,2] row_mask:0xf bank_mask:0xf bound_ctrl:1
	v_add_f32_dpp v0, v0, v0 quad_perm:[1,0,3,2] row_mask:0xf bank_mask:0xf bound_ctrl:1
	v_and_b32_e32 v51, 0xffff0000, v34
	v_add_f32_dpp v5, v5, v5 quad_perm:[2,3,0,1] row_mask:0xf bank_mask:0xf bound_ctrl:1
	v_add_f32_dpp v0, v0, v0 quad_perm:[2,3,0,1] row_mask:0xf bank_mask:0xf bound_ctrl:1
	v_lshlrev_b32_e32 v34, 16, v35
	v_add_f32_dpp v5, v5, v5 row_half_mirror row_mask:0xf bank_mask:0xf bound_ctrl:1
	v_add_f32_dpp v0, v0, v0 row_half_mirror row_mask:0xf bank_mask:0xf bound_ctrl:1
	v_and_b32_e32 v35, 0xffff0000, v35
	v_add_f32_dpp v5, v5, v5 row_ror:8 row_mask:0xf bank_mask:0xf bound_ctrl:1
	v_fmamk_f32 v5, v5, 0x3c800000, v3
	v_mul_f32_e32 v14, 0x4f800000, v5
	v_cmp_gt_f32_e32 vcc, s24, v5
	v_add_f32_dpp v0, v0, v0 row_ror:8 row_mask:0xf bank_mask:0xf bound_ctrl:1
	v_lshlrev_b32_e32 v52, 16, v36
	v_cndmask_b32_e32 v5, v5, v14, vcc
	v_sqrt_f32_e32 v14, v5
	v_and_b32_e32 v53, 0xffff0000, v36
	v_lshlrev_b32_e32 v36, 16, v37
	v_and_b32_e32 v37, 0xffff0000, v37
	v_add_u32_e32 v15, -1, v14
	v_add_u32_e32 v16, 1, v14
	v_fma_f32 v17, -v15, v14, v5
	v_fma_f32 v18, -v16, v14, v5
	v_cmp_ge_f32_e64 s[6:7], 0, v17
	s_nop 1
	v_cndmask_b32_e64 v14, v14, v15, s[6:7]
	v_cmp_lt_f32_e64 s[6:7], 0, v18
	s_nop 1
	v_cndmask_b32_e64 v14, v14, v16, s[6:7]
	v_mul_f32_e32 v15, 0x37800000, v14
	v_cndmask_b32_e32 v14, v14, v15, vcc
	v_cmp_class_f32_e32 vcc, v5, v4
	s_nop 1
	v_cndmask_b32_e32 v5, v14, v5, vcc
	v_div_scale_f32 v14, s[0:1], v5, v5, 1.0
	v_rcp_f32_e32 v16, v14
	v_div_scale_f32 v15, vcc, 1.0, v5, 1.0
	v_fma_f32 v17, -v14, v16, 1.0
	v_fmac_f32_e32 v16, v17, v16
	v_mul_f32_e32 v17, v15, v16
	v_fma_f32 v18, -v14, v17, v15
	v_fmac_f32_e32 v17, v18, v16
	v_fma_f32 v14, -v14, v17, v15
	v_div_fmas_f32 v14, v14, v16, v17
	v_div_fixup_f32 v14, v14, v5, 1.0
	v_pk_mul_f32 v[16:17], v[30:31], v[14:15] op_sel_hi:[1,0]
	v_pk_mul_f32 v[14:15], v[28:29], v[14:15] op_sel_hi:[1,0]
	v_pk_fma_f32 v[6:7], v[6:7], v[16:17], v[10:11]
	v_pk_fma_f32 v[8:9], v[8:9], v[14:15], v[12:13]
	v_pk_fma_f32 v[6:7], v[0:1], v[50:51], v[6:7] op_sel_hi:[0,1,1]
	v_pk_fma_f32 v[8:9], v[0:1], v[34:35], v[8:9] op_sel_hi:[0,1,1]
	v_pk_mul_f32 v[6:7], v[6:7], v[52:53]
	v_pk_mul_f32 v[8:9], v[8:9], v[36:37]
	s_nop 1
	v_cvt_pk_bf16_f32 v6, v6, v7
	s_nop 0
	s_nop 1
	v_cvt_pk_bf16_f32 v7, v8, v9
	global_store_dwordx2 v26, v[6:7], s[8:9]
	s_sub_u32 s4, s4, 1
	s_cmp_lg_u32 s4, 0
	s_cbranch_scc1 .Lp6_loop
